# v005 + SwiGLU epilogues (P7/P12): rstd of all 8 row groups computed in one batch after the ALIGN barrier instead of 8 serialized bpermute/rsq chains
# speedup vs baseline: 1.0125x; 1.0022x over previous
; __device__ __forceinline__ unsigned cvt_pk_bf16(float lo, float hi) { const cvt_f32x2_t v = {lo, hi}; const cvt_bf16x2_t b = __builtin_convertvector(v, cvt_bf16x2_t); return __builtin_bit_cast(unsigned, b); }
; __device__ __forceinline__ float silu_mul(float g, float u) { return g * u * __builtin_amdgcn_rcpf(1.0f + __builtin_amdgcn_exp2f(g * -1.4426950408889634f)); }
; __device__ __forceinline__ float rstd_from_slots(const float* slots, int row, int fq) {
;     const f32x4 s4 = *(const f32x4*)(slots + (size_t)row * 16 + 4 * fq);
;     float s = (s4[0] + s4[1]) + (s4[2] + s4[3]);
;     s += __shfl_xor(s, 16); s += __shfl_xor(s, 32);
;     return __builtin_amdgcn_rsqf(s * (1.0f / 1024.0f) + RMS_EPS_F);
; }
;     __device__ __forceinline__ void operator()(const f32x4 (&acc)[2][2][4][2], const Unit& u, int wr, int wc, int fr, int fq) const {
;         const int row0 = u.pm * BM + wr * 64 + fr; const int col0 = u.pn * HALF + wc * 32 + 8 * fq;
; #pragma unroll
;         for (int ai = 0; ai < 2; ++ai)
; #pragma unroll
;             for (int m = 0; m < 4; ++m) { const int row = row0 + ai * HALF + m * 16;
;                 const float sc = rstd_from_slots(slots, row, fq);
;                 const f32x4 g0 = acc[ai][0][m][0] * sc, g1 = acc[ai][0][m][1] * sc, u0 = acc[ai][1][m][0] * sc, u1 = acc[ai][1][m][1] * sc;
;                 u32x4 w; w.x = cvt_pk_bf16(silu_mul(g0[0], u0[0]), silu_mul(g0[1], u0[1])); w.y = cvt_pk_bf16(silu_mul(g0[2], u0[2]), silu_mul(g0[3], u0[3]));
;                 w.z = cvt_pk_bf16(silu_mul(g1[0], u1[0]), silu_mul(g1[1], u1[1])); w.w = cvt_pk_bf16(silu_mul(g1[2], u1[2]), silu_mul(g1[3], u1[3]));
;                 __builtin_nontemporal_store(w, (u32x4*)(O + (size_t)row * ldc + col0)); }
.LBB0_675:
	v_xor_b32_e32 v216, 16, v161
	v_xor_b32_e32 v217, 32, v161
	v_lshlrev_b32_e32 v216, 2, v216
	v_lshlrev_b32_e32 v217, 2, v217
	s_waitcnt vmcnt(0)
	v_add_f32_e32 v172, v172, v173
	v_add_f32_e32 v173, v175, v174
	v_add_f32_e32 v176, v176, v177
	v_add_f32_e32 v177, v179, v178
	v_add_f32_e32 v180, v180, v181
	v_add_f32_e32 v181, v183, v182
	v_add_f32_e32 v184, v184, v185
	v_add_f32_e32 v185, v187, v186
	v_add_f32_e32 v188, v188, v189
	v_add_f32_e32 v189, v191, v190
	v_add_f32_e32 v192, v192, v193
	v_add_f32_e32 v193, v195, v194
	v_add_f32_e32 v196, v196, v197
	v_add_f32_e32 v197, v199, v198
	v_add_f32_e32 v200, v200, v201
	v_add_f32_e32 v201, v203, v202
	v_add_f32_e32 v172, v172, v173
	v_add_f32_e32 v176, v176, v177
	v_add_f32_e32 v180, v180, v181
	v_add_f32_e32 v184, v184, v185
	v_add_f32_e32 v188, v188, v189
	v_add_f32_e32 v192, v192, v193
	v_add_f32_e32 v196, v196, v197
	v_add_f32_e32 v200, v200, v201
	ds_bpermute_b32 v173, v216, v172
	ds_bpermute_b32 v177, v216, v176
	ds_bpermute_b32 v181, v216, v180
	ds_bpermute_b32 v185, v216, v184
	ds_bpermute_b32 v189, v216, v188
	ds_bpermute_b32 v193, v216, v192
	ds_bpermute_b32 v197, v216, v196
	ds_bpermute_b32 v201, v216, v200
	s_waitcnt lgkmcnt(0)
	v_add_f32_e32 v172, v172, v173
	v_add_f32_e32 v176, v176, v177
	v_add_f32_e32 v180, v180, v181
	v_add_f32_e32 v184, v184, v185
	v_add_f32_e32 v188, v188, v189
	v_add_f32_e32 v192, v192, v193
	v_add_f32_e32 v196, v196, v197
	v_add_f32_e32 v200, v200, v201
	ds_bpermute_b32 v173, v217, v172
	ds_bpermute_b32 v177, v217, v176
	ds_bpermute_b32 v181, v217, v180
	ds_bpermute_b32 v185, v217, v184
	ds_bpermute_b32 v189, v217, v188
	ds_bpermute_b32 v193, v217, v192
	ds_bpermute_b32 v197, v217, v196
	ds_bpermute_b32 v201, v217, v200
	s_waitcnt lgkmcnt(0)
	v_add_f32_e32 v172, v172, v173
	v_add_f32_e32 v176, v176, v177
	v_add_f32_e32 v180, v180, v181
	v_add_f32_e32 v184, v184, v185
	v_add_f32_e32 v188, v188, v189
	v_add_f32_e32 v192, v192, v193
	v_add_f32_e32 v196, v196, v197
	v_add_f32_e32 v200, v200, v201
	v_fmamk_f32 v172, v172, 0x3a800000, v162
	v_fmamk_f32 v176, v176, 0x3a800000, v162
	v_fmamk_f32 v180, v180, 0x3a800000, v162
	v_fmamk_f32 v184, v184, 0x3a800000, v162
	v_fmamk_f32 v188, v188, 0x3a800000, v162
	v_fmamk_f32 v192, v192, 0x3a800000, v162
	v_fmamk_f32 v196, v196, 0x3a800000, v162
	v_fmamk_f32 v200, v200, 0x3a800000, v162
	v_rsq_f32_e32 v172, v172
	v_rsq_f32_e32 v176, v176
	v_rsq_f32_e32 v180, v180
	v_rsq_f32_e32 v184, v184
	v_rsq_f32_e32 v188, v188
	v_rsq_f32_e32 v192, v192
	v_rsq_f32_e32 v196, v196
	v_rsq_f32_e32 v200, v200
	v_lshl_add_u32 v150, s0, 8, v152
	v_ashrrev_i32_e32 v151, 31, v150
	v_lshlrev_b64 v[146:147], 6, v[150:151]
	v_lshl_add_u64 v[146:147], v[136:137], 0, v[146:147]
	v_and_b32_e32 v151, 64, v161
	v_xor_b32_e32 v149, 16, v161
	v_add_u32_e32 v170, 64, v151
	v_cmp_lt_i32_e32 vcc, v149, v170
	v_xor_b32_e32 v163, 32, v161
	v_lshl_or_b32 v148, s1, 7, v157
	v_cndmask_b32_e32 v149, v161, v149, vcc
	v_lshlrev_b32_e32 v151, 2, v149
	v_cmp_lt_i32_e32 vcc, v163, v170
	v_mov_b64_e32 v[146:147], s[10:11]
	v_ashrrev_i32_e32 v149, 31, v148
	v_cndmask_b32_e32 v163, v161, v163, vcc
	v_lshlrev_b32_e32 v163, 2, v163
	v_lshlrev_b64 v[148:149], 1, v[148:149]
	s_andn2_b64 vcc, exec, s[2:3]
	v_or_b32_e32 v166, 16, v150
	v_ashrrev_i32_e32 v167, 31, v166
	v_lshlrev_b64 v[170:171], 6, v[166:167]
	v_lshl_add_u64 v[170:171], v[136:137], 0, v[170:171]
	v_mad_i64_i32 v[164:165], s[0:1], v150, s56, v[146:147]
	v_lshl_add_u64 v[164:165], v[164:165], 0, v[148:149]
	v_mov_b32_e32 v168, v172
	v_pk_mul_f32 v[126:127], v[126:127], v[168:169] op_sel_hi:[1,0]
	v_pk_mul_f32 v[124:125], v[124:125], v[168:169] op_sel_hi:[1,0]
	v_pk_mul_f32 v[122:123], v[122:123], v[168:169] op_sel_hi:[1,0]
	v_pk_mul_f32 v[120:121], v[120:121], v[168:169] op_sel_hi:[1,0]
	v_pk_mul_f32 v[116:117], v[116:117], v[168:169] op_sel_hi:[1,0]
	v_pk_mul_f32 v[118:119], v[118:119], v[168:169] op_sel_hi:[1,0]
	v_pk_mul_f32 v[112:113], v[112:113], v[168:169] op_sel_hi:[1,0]
	v_pk_mul_f32 v[114:115], v[114:115], v[168:169] op_sel_hi:[1,0]
	v_mul_f32_e32 v167, 0xbfb8aa3b, v124
	v_mul_f32_e32 v168, 0xbfb8aa3b, v125
	v_pk_mul_f32 v[118:119], v[126:127], v[118:119]
	v_pk_mul_f32 v[116:117], v[124:125], v[116:117]
	v_mul_f32_e32 v124, 0xbfb8aa3b, v126
	v_mul_f32_e32 v125, 0xbfb8aa3b, v127
	v_mul_f32_e32 v126, 0xbfb8aa3b, v120
	v_mul_f32_e32 v127, 0xbfb8aa3b, v121
	v_pk_mul_f32 v[112:113], v[120:121], v[112:113]
	v_mul_f32_e32 v120, 0xbfb8aa3b, v122
	v_mul_f32_e32 v121, 0xbfb8aa3b, v123
	v_pk_mul_f32 v[114:115], v[122:123], v[114:115]
	v_exp_f32_e32 v122, v167
	v_exp_f32_e32 v123, v168
	v_exp_f32_e32 v124, v124
	v_exp_f32_e32 v125, v125
	v_exp_f32_e32 v126, v126
	v_exp_f32_e32 v127, v127
	v_exp_f32_e32 v120, v120
	v_exp_f32_e32 v121, v121
	v_add_f32_e32 v122, 1.0, v122
	v_add_f32_e32 v123, 1.0, v123
	v_add_f32_e32 v124, 1.0, v124
	v_add_f32_e32 v125, 1.0, v125
	v_add_f32_e32 v126, 1.0, v126
	v_add_f32_e32 v127, 1.0, v127
	v_add_f32_e32 v167, 1.0, v120
	v_add_f32_e32 v168, 1.0, v121
	v_rcp_f32_e32 v120, v122
	v_rcp_f32_e32 v121, v123
	v_rcp_f32_e32 v122, v124
	v_rcp_f32_e32 v123, v125
	v_rcp_f32_e32 v124, v126
	v_rcp_f32_e32 v125, v127
	v_rcp_f32_e32 v126, v167
	v_rcp_f32_e32 v127, v168
	v_pk_mul_f32 v[116:117], v[116:117], v[120:121]
	v_pk_mul_f32 v[118:119], v[118:119], v[122:123]
	v_pk_mul_f32 v[120:121], v[112:113], v[124:125]
	v_pk_mul_f32 v[122:123], v[114:115], v[126:127]
	v_cvt_pk_bf16_f32 v112, v116, v117
	v_cvt_pk_bf16_f32 v113, v118, v119
	v_cvt_pk_bf16_f32 v114, v120, v121
	v_cvt_pk_bf16_f32 v115, v122, v123
	global_store_dwordx4 v[164:165], v[112:115], off nt
	s_nop 1
; __device__ __forceinline__ unsigned cvt_pk_bf16(float lo, float hi) { const cvt_f32x2_t v = {lo, hi}; const cvt_bf16x2_t b = __builtin_convertvector(v, cvt_bf16x2_t); return __builtin_bit_cast(unsigned, b); }
; __device__ __forceinline__ float silu_mul(float g, float u) { return g * u * __builtin_amdgcn_rcpf(1.0f + __builtin_amdgcn_exp2f(g * -1.4426950408889634f)); }
;     __device__ __forceinline__ void operator()(const f32x4 (&acc)[2][2][4][2], const Unit& u, int wr, int wc, int fr, int fq) const {
;     ...
;             for (int m = 0; m < 4; ++m) { const int row = row0 + ai * HALF + m * 16;
;                 const float sc = rstd_from_slots(slots, row, fq);
;                 const f32x4 g0 = acc[ai][0][m][0] * sc, g1 = acc[ai][0][m][1] * sc, u0 = acc[ai][1][m][0] * sc, u1 = acc[ai][1][m][1] * sc;
;                 u32x4 w; w.x = cvt_pk_bf16(silu_mul(g0[0], u0[0]), silu_mul(g0[1], u0[1])); w.y = cvt_pk_bf16(silu_mul(g0[2], u0[2]), silu_mul(g0[3], u0[3]));
;                 w.z = cvt_pk_bf16(silu_mul(g1[0], u1[0]), silu_mul(g1[1], u1[1])); w.w = cvt_pk_bf16(silu_mul(g1[2], u1[2]), silu_mul(g1[3], u1[3]));
;                 __builtin_nontemporal_store(w, (u32x4*)(O + (size_t)row * ldc + col0)); }
	v_mad_i64_i32 v[114:115], s[0:1], v166, s56, v[146:147]
	v_lshl_add_u64 v[114:115], v[114:115], 0, v[148:149]
	v_or_b32_e32 v112, 32, v150
	v_ashrrev_i32_e32 v113, 31, v112
	v_lshlrev_b64 v[118:119], 6, v[112:113]
	v_lshl_add_u64 v[118:119], v[136:137], 0, v[118:119]
	v_mov_b32_e32 v116, v176
	v_pk_mul_f32 v[110:111], v[110:111], v[116:117] op_sel_hi:[1,0]
	v_pk_mul_f32 v[108:109], v[108:109], v[116:117] op_sel_hi:[1,0]
	v_pk_mul_f32 v[106:107], v[106:107], v[116:117] op_sel_hi:[1,0]
	v_pk_mul_f32 v[104:105], v[104:105], v[116:117] op_sel_hi:[1,0]
	v_pk_mul_f32 v[100:101], v[100:101], v[116:117] op_sel_hi:[1,0]
	v_pk_mul_f32 v[102:103], v[102:103], v[116:117] op_sel_hi:[1,0]
	v_pk_mul_f32 v[96:97], v[96:97], v[116:117] op_sel_hi:[1,0]
	v_pk_mul_f32 v[98:99], v[98:99], v[116:117] op_sel_hi:[1,0]
	v_mul_f32_e32 v113, 0xbfb8aa3b, v108
	v_mul_f32_e32 v116, 0xbfb8aa3b, v109
	v_pk_mul_f32 v[102:103], v[110:111], v[102:103]
	v_pk_mul_f32 v[100:101], v[108:109], v[100:101]
	v_mul_f32_e32 v108, 0xbfb8aa3b, v110
	v_mul_f32_e32 v109, 0xbfb8aa3b, v111
	v_mul_f32_e32 v110, 0xbfb8aa3b, v104
	v_mul_f32_e32 v111, 0xbfb8aa3b, v105
	v_pk_mul_f32 v[96:97], v[104:105], v[96:97]
	v_mul_f32_e32 v104, 0xbfb8aa3b, v106
	v_mul_f32_e32 v105, 0xbfb8aa3b, v107
	v_pk_mul_f32 v[98:99], v[106:107], v[98:99]
	v_exp_f32_e32 v106, v113
	v_exp_f32_e32 v107, v116
	v_exp_f32_e32 v108, v108
	v_exp_f32_e32 v109, v109
	v_exp_f32_e32 v110, v110
	v_exp_f32_e32 v111, v111
	v_exp_f32_e32 v104, v104
	v_exp_f32_e32 v105, v105
	v_add_f32_e32 v106, 1.0, v106
	v_add_f32_e32 v107, 1.0, v107
	v_add_f32_e32 v108, 1.0, v108
	v_add_f32_e32 v109, 1.0, v109
	v_add_f32_e32 v110, 1.0, v110
	v_add_f32_e32 v111, 1.0, v111
	v_add_f32_e32 v113, 1.0, v104
	v_add_f32_e32 v116, 1.0, v105
	v_rcp_f32_e32 v104, v106
	v_rcp_f32_e32 v105, v107
	v_rcp_f32_e32 v106, v108
	v_rcp_f32_e32 v107, v109
	v_rcp_f32_e32 v108, v110
	v_rcp_f32_e32 v109, v111
	v_rcp_f32_e32 v110, v113
	v_rcp_f32_e32 v111, v116
	v_pk_mul_f32 v[100:101], v[100:101], v[104:105]
	v_pk_mul_f32 v[102:103], v[102:103], v[106:107]
	v_pk_mul_f32 v[104:105], v[96:97], v[108:109]
	v_pk_mul_f32 v[106:107], v[98:99], v[110:111]
	v_cvt_pk_bf16_f32 v96, v100, v101
	v_cvt_pk_bf16_f32 v97, v102, v103
	v_cvt_pk_bf16_f32 v98, v104, v105
	v_cvt_pk_bf16_f32 v99, v106, v107
	global_store_dwordx4 v[114:115], v[96:99], off nt
	s_nop 1
	v_mad_i64_i32 v[98:99], s[0:1], v112, s56, v[146:147]
	v_lshl_add_u64 v[98:99], v[98:99], 0, v[148:149]
	v_or_b32_e32 v96, 48, v150
	v_ashrrev_i32_e32 v97, 31, v96
	v_lshlrev_b64 v[102:103], 6, v[96:97]
	v_lshl_add_u64 v[102:103], v[136:137], 0, v[102:103]
	v_mov_b32_e32 v100, v180
	v_pk_mul_f32 v[94:95], v[94:95], v[100:101] op_sel_hi:[1,0]
	v_pk_mul_f32 v[92:93], v[92:93], v[100:101] op_sel_hi:[1,0]
	v_pk_mul_f32 v[90:91], v[90:91], v[100:101] op_sel_hi:[1,0]
	v_pk_mul_f32 v[88:89], v[88:89], v[100:101] op_sel_hi:[1,0]
	v_pk_mul_f32 v[84:85], v[84:85], v[100:101] op_sel_hi:[1,0]
	v_pk_mul_f32 v[86:87], v[86:87], v[100:101] op_sel_hi:[1,0]
	v_pk_mul_f32 v[80:81], v[80:81], v[100:101] op_sel_hi:[1,0]
	v_pk_mul_f32 v[82:83], v[82:83], v[100:101] op_sel_hi:[1,0]
	v_mul_f32_e32 v97, 0xbfb8aa3b, v92
	v_mul_f32_e32 v100, 0xbfb8aa3b, v93
	v_pk_mul_f32 v[86:87], v[94:95], v[86:87]
	v_pk_mul_f32 v[84:85], v[92:93], v[84:85]
	v_mul_f32_e32 v92, 0xbfb8aa3b, v94
	v_mul_f32_e32 v93, 0xbfb8aa3b, v95
	v_mul_f32_e32 v94, 0xbfb8aa3b, v88
	v_mul_f32_e32 v95, 0xbfb8aa3b, v89
	v_pk_mul_f32 v[80:81], v[88:89], v[80:81]
	v_mul_f32_e32 v88, 0xbfb8aa3b, v90
	v_mul_f32_e32 v89, 0xbfb8aa3b, v91
	v_pk_mul_f32 v[82:83], v[90:91], v[82:83]
	v_exp_f32_e32 v90, v97
	v_exp_f32_e32 v91, v100
	v_exp_f32_e32 v92, v92
	v_exp_f32_e32 v93, v93
	v_exp_f32_e32 v94, v94
	v_exp_f32_e32 v95, v95
	v_exp_f32_e32 v88, v88
	v_exp_f32_e32 v89, v89
	v_add_f32_e32 v90, 1.0, v90
	v_add_f32_e32 v91, 1.0, v91
	v_add_f32_e32 v92, 1.0, v92
	v_add_f32_e32 v93, 1.0, v93
	v_add_f32_e32 v94, 1.0, v94
	v_add_f32_e32 v95, 1.0, v95
	v_add_f32_e32 v97, 1.0, v88
	v_add_f32_e32 v100, 1.0, v89
	v_rcp_f32_e32 v88, v90
	v_rcp_f32_e32 v89, v91
	v_rcp_f32_e32 v90, v92
	v_rcp_f32_e32 v91, v93
	v_rcp_f32_e32 v92, v94
	v_rcp_f32_e32 v93, v95
	v_rcp_f32_e32 v94, v97
	v_rcp_f32_e32 v95, v100
	v_pk_mul_f32 v[84:85], v[84:85], v[88:89]
	v_pk_mul_f32 v[86:87], v[86:87], v[90:91]
	v_pk_mul_f32 v[88:89], v[80:81], v[92:93]
	v_pk_mul_f32 v[90:91], v[82:83], v[94:95]
	v_cvt_pk_bf16_f32 v80, v84, v85
	v_cvt_pk_bf16_f32 v81, v86, v87
	v_cvt_pk_bf16_f32 v82, v88, v89
	v_cvt_pk_bf16_f32 v83, v90, v91
	global_store_dwordx4 v[98:99], v[80:83], off nt
	s_nop 1
	v_mad_i64_i32 v[82:83], s[0:1], v96, s56, v[146:147]
	v_lshl_add_u64 v[82:83], v[82:83], 0, v[148:149]
	v_add_u32_e32 v80, 0x80, v150
	v_ashrrev_i32_e32 v81, 31, v80
	v_lshlrev_b64 v[86:87], 6, v[80:81]
	v_lshl_add_u64 v[86:87], v[136:137], 0, v[86:87]
	v_mov_b32_e32 v84, v184
	v_pk_mul_f32 v[78:79], v[78:79], v[84:85] op_sel_hi:[1,0]
	v_pk_mul_f32 v[76:77], v[76:77], v[84:85] op_sel_hi:[1,0]
	v_pk_mul_f32 v[74:75], v[74:75], v[84:85] op_sel_hi:[1,0]
	v_pk_mul_f32 v[72:73], v[72:73], v[84:85] op_sel_hi:[1,0]
	v_pk_mul_f32 v[68:69], v[68:69], v[84:85] op_sel_hi:[1,0]
	v_pk_mul_f32 v[70:71], v[70:71], v[84:85] op_sel_hi:[1,0]
	v_pk_mul_f32 v[64:65], v[64:65], v[84:85] op_sel_hi:[1,0]
	v_pk_mul_f32 v[66:67], v[66:67], v[84:85] op_sel_hi:[1,0]
	v_mul_f32_e32 v81, 0xbfb8aa3b, v76
	v_mul_f32_e32 v84, 0xbfb8aa3b, v77
	v_pk_mul_f32 v[70:71], v[78:79], v[70:71]
	v_pk_mul_f32 v[68:69], v[76:77], v[68:69]
	v_mul_f32_e32 v76, 0xbfb8aa3b, v78
	v_mul_f32_e32 v77, 0xbfb8aa3b, v79
	v_mul_f32_e32 v78, 0xbfb8aa3b, v72
	v_mul_f32_e32 v79, 0xbfb8aa3b, v73
; __device__ __forceinline__ unsigned cvt_pk_bf16(float lo, float hi) { const cvt_f32x2_t v = {lo, hi}; const cvt_bf16x2_t b = __builtin_convertvector(v, cvt_bf16x2_t); return __builtin_bit_cast(unsigned, b); }
; __device__ __forceinline__ float silu_mul(float g, float u) { return g * u * __builtin_amdgcn_rcpf(1.0f + __builtin_amdgcn_exp2f(g * -1.4426950408889634f)); }
;     __device__ __forceinline__ void operator()(const f32x4 (&acc)[2][2][4][2], const Unit& u, int wr, int wc, int fr, int fq) const {
;     ...
;             for (int m = 0; m < 4; ++m) { const int row = row0 + ai * HALF + m * 16;
;                 const float sc = rstd_from_slots(slots, row, fq);
;                 const f32x4 g0 = acc[ai][0][m][0] * sc, g1 = acc[ai][0][m][1] * sc, u0 = acc[ai][1][m][0] * sc, u1 = acc[ai][1][m][1] * sc;
;                 u32x4 w; w.x = cvt_pk_bf16(silu_mul(g0[0], u0[0]), silu_mul(g0[1], u0[1])); w.y = cvt_pk_bf16(silu_mul(g0[2], u0[2]), silu_mul(g0[3], u0[3]));
;                 w.z = cvt_pk_bf16(silu_mul(g1[0], u1[0]), silu_mul(g1[1], u1[1])); w.w = cvt_pk_bf16(silu_mul(g1[2], u1[2]), silu_mul(g1[3], u1[3]));
;                 __builtin_nontemporal_store(w, (u32x4*)(O + (size_t)row * ldc + col0)); }
	v_pk_mul_f32 v[64:65], v[72:73], v[64:65]
	v_mul_f32_e32 v72, 0xbfb8aa3b, v74
	v_mul_f32_e32 v73, 0xbfb8aa3b, v75
	v_pk_mul_f32 v[66:67], v[74:75], v[66:67]
	v_exp_f32_e32 v74, v81
	v_exp_f32_e32 v75, v84
	v_exp_f32_e32 v76, v76
	v_exp_f32_e32 v77, v77
	v_exp_f32_e32 v78, v78
	v_exp_f32_e32 v79, v79
	v_exp_f32_e32 v72, v72
	v_exp_f32_e32 v73, v73
	v_add_f32_e32 v74, 1.0, v74
	v_add_f32_e32 v75, 1.0, v75
	v_add_f32_e32 v76, 1.0, v76
	v_add_f32_e32 v77, 1.0, v77
	v_add_f32_e32 v78, 1.0, v78
	v_add_f32_e32 v79, 1.0, v79
	v_add_f32_e32 v81, 1.0, v72
	v_add_f32_e32 v84, 1.0, v73
	v_rcp_f32_e32 v72, v74
	v_rcp_f32_e32 v73, v75
	v_rcp_f32_e32 v74, v76
	v_rcp_f32_e32 v75, v77
	v_rcp_f32_e32 v76, v78
	v_rcp_f32_e32 v77, v79
	v_rcp_f32_e32 v78, v81
	v_rcp_f32_e32 v79, v84
	v_pk_mul_f32 v[68:69], v[68:69], v[72:73]
	v_pk_mul_f32 v[70:71], v[70:71], v[74:75]
	v_pk_mul_f32 v[72:73], v[64:65], v[76:77]
	v_pk_mul_f32 v[74:75], v[66:67], v[78:79]
	v_cvt_pk_bf16_f32 v64, v68, v69
	v_cvt_pk_bf16_f32 v65, v70, v71
	v_cvt_pk_bf16_f32 v66, v72, v73
	v_cvt_pk_bf16_f32 v67, v74, v75
	global_store_dwordx4 v[82:83], v[64:67], off nt
	s_nop 1
	v_mad_i64_i32 v[66:67], s[0:1], v80, s56, v[146:147]
	v_lshl_add_u64 v[66:67], v[66:67], 0, v[148:149]
	v_add_u32_e32 v64, 0x90, v150
	v_ashrrev_i32_e32 v65, 31, v64
	v_lshlrev_b64 v[70:71], 6, v[64:65]
	v_lshl_add_u64 v[70:71], v[136:137], 0, v[70:71]
	v_mov_b32_e32 v68, v188
	v_pk_mul_f32 v[62:63], v[62:63], v[68:69] op_sel_hi:[1,0]
	v_pk_mul_f32 v[60:61], v[60:61], v[68:69] op_sel_hi:[1,0]
	v_pk_mul_f32 v[58:59], v[58:59], v[68:69] op_sel_hi:[1,0]
	v_pk_mul_f32 v[56:57], v[56:57], v[68:69] op_sel_hi:[1,0]
	v_pk_mul_f32 v[52:53], v[52:53], v[68:69] op_sel_hi:[1,0]
	v_pk_mul_f32 v[54:55], v[54:55], v[68:69] op_sel_hi:[1,0]
	v_pk_mul_f32 v[48:49], v[48:49], v[68:69] op_sel_hi:[1,0]
	v_pk_mul_f32 v[50:51], v[50:51], v[68:69] op_sel_hi:[1,0]
	v_mul_f32_e32 v65, 0xbfb8aa3b, v60
	v_mul_f32_e32 v68, 0xbfb8aa3b, v61
	v_pk_mul_f32 v[54:55], v[62:63], v[54:55]
	v_pk_mul_f32 v[52:53], v[60:61], v[52:53]
	v_mul_f32_e32 v60, 0xbfb8aa3b, v62
	v_mul_f32_e32 v61, 0xbfb8aa3b, v63
	v_mul_f32_e32 v62, 0xbfb8aa3b, v56
	v_mul_f32_e32 v63, 0xbfb8aa3b, v57
	v_pk_mul_f32 v[48:49], v[56:57], v[48:49]
	v_mul_f32_e32 v56, 0xbfb8aa3b, v58
	v_mul_f32_e32 v57, 0xbfb8aa3b, v59
	v_pk_mul_f32 v[50:51], v[58:59], v[50:51]
	v_exp_f32_e32 v58, v65
	v_exp_f32_e32 v59, v68
	v_exp_f32_e32 v60, v60
	v_exp_f32_e32 v61, v61
	v_exp_f32_e32 v62, v62
	v_exp_f32_e32 v63, v63
	v_exp_f32_e32 v56, v56
	v_exp_f32_e32 v57, v57
	v_add_f32_e32 v58, 1.0, v58
	v_add_f32_e32 v59, 1.0, v59
	v_add_f32_e32 v60, 1.0, v60
	v_add_f32_e32 v61, 1.0, v61
	v_add_f32_e32 v62, 1.0, v62
	v_add_f32_e32 v63, 1.0, v63
	v_add_f32_e32 v65, 1.0, v56
	v_add_f32_e32 v68, 1.0, v57
	v_rcp_f32_e32 v56, v58
	v_rcp_f32_e32 v57, v59
	v_rcp_f32_e32 v58, v60
	v_rcp_f32_e32 v59, v61
	v_rcp_f32_e32 v60, v62
	v_rcp_f32_e32 v61, v63
	v_rcp_f32_e32 v62, v65
	v_rcp_f32_e32 v63, v68
	v_pk_mul_f32 v[52:53], v[52:53], v[56:57]
	v_pk_mul_f32 v[54:55], v[54:55], v[58:59]
	v_pk_mul_f32 v[56:57], v[48:49], v[60:61]
	v_pk_mul_f32 v[58:59], v[50:51], v[62:63]
	v_cvt_pk_bf16_f32 v48, v52, v53
	v_cvt_pk_bf16_f32 v49, v54, v55
	v_cvt_pk_bf16_f32 v50, v56, v57
	v_cvt_pk_bf16_f32 v51, v58, v59
	global_store_dwordx4 v[66:67], v[48:51], off nt
	s_nop 1
	v_mad_i64_i32 v[50:51], s[0:1], v64, s56, v[146:147]
	v_lshl_add_u64 v[50:51], v[50:51], 0, v[148:149]
	v_add_u32_e32 v48, 0xa0, v150
	v_ashrrev_i32_e32 v49, 31, v48
	v_lshlrev_b64 v[54:55], 6, v[48:49]
	v_lshl_add_u64 v[54:55], v[136:137], 0, v[54:55]
	v_mov_b32_e32 v52, v192
	v_pk_mul_f32 v[46:47], v[46:47], v[52:53] op_sel_hi:[1,0]
	v_pk_mul_f32 v[44:45], v[44:45], v[52:53] op_sel_hi:[1,0]
	v_pk_mul_f32 v[42:43], v[42:43], v[52:53] op_sel_hi:[1,0]
	v_pk_mul_f32 v[40:41], v[40:41], v[52:53] op_sel_hi:[1,0]
	v_pk_mul_f32 v[36:37], v[36:37], v[52:53] op_sel_hi:[1,0]
	v_pk_mul_f32 v[38:39], v[38:39], v[52:53] op_sel_hi:[1,0]
	v_pk_mul_f32 v[32:33], v[32:33], v[52:53] op_sel_hi:[1,0]
	v_pk_mul_f32 v[34:35], v[34:35], v[52:53] op_sel_hi:[1,0]
	v_mul_f32_e32 v49, 0xbfb8aa3b, v44
	v_mul_f32_e32 v52, 0xbfb8aa3b, v45
	v_pk_mul_f32 v[38:39], v[46:47], v[38:39]
	v_pk_mul_f32 v[36:37], v[44:45], v[36:37]
	v_mul_f32_e32 v44, 0xbfb8aa3b, v46
	v_mul_f32_e32 v45, 0xbfb8aa3b, v47
	v_mul_f32_e32 v46, 0xbfb8aa3b, v40
	v_mul_f32_e32 v47, 0xbfb8aa3b, v41
	v_pk_mul_f32 v[32:33], v[40:41], v[32:33]
	v_mul_f32_e32 v40, 0xbfb8aa3b, v42
	v_mul_f32_e32 v41, 0xbfb8aa3b, v43
	v_pk_mul_f32 v[34:35], v[42:43], v[34:35]
	v_exp_f32_e32 v42, v49
	v_exp_f32_e32 v43, v52
	v_exp_f32_e32 v44, v44
	v_exp_f32_e32 v45, v45
	v_exp_f32_e32 v46, v46
	v_exp_f32_e32 v47, v47
	v_exp_f32_e32 v40, v40
	v_exp_f32_e32 v41, v41
	v_add_f32_e32 v42, 1.0, v42
	v_add_f32_e32 v43, 1.0, v43
	v_add_f32_e32 v44, 1.0, v44
	v_add_f32_e32 v45, 1.0, v45
	v_add_f32_e32 v46, 1.0, v46
	v_add_f32_e32 v47, 1.0, v47
; __device__ __forceinline__ unsigned cvt_pk_bf16(float lo, float hi) { const cvt_f32x2_t v = {lo, hi}; const cvt_bf16x2_t b = __builtin_convertvector(v, cvt_bf16x2_t); return __builtin_bit_cast(unsigned, b); }
; __device__ __forceinline__ float silu_mul(float g, float u) { return g * u * __builtin_amdgcn_rcpf(1.0f + __builtin_amdgcn_exp2f(g * -1.4426950408889634f)); }
;     __device__ __forceinline__ void operator()(const f32x4 (&acc)[2][2][4][2], const Unit& u, int wr, int wc, int fr, int fq) const {
;     ...
;             for (int m = 0; m < 4; ++m) { const int row = row0 + ai * HALF + m * 16;
;                 const float sc = rstd_from_slots(slots, row, fq);
;                 const f32x4 g0 = acc[ai][0][m][0] * sc, g1 = acc[ai][0][m][1] * sc, u0 = acc[ai][1][m][0] * sc, u1 = acc[ai][1][m][1] * sc;
;                 u32x4 w; w.x = cvt_pk_bf16(silu_mul(g0[0], u0[0]), silu_mul(g0[1], u0[1])); w.y = cvt_pk_bf16(silu_mul(g0[2], u0[2]), silu_mul(g0[3], u0[3]));
;                 w.z = cvt_pk_bf16(silu_mul(g1[0], u1[0]), silu_mul(g1[1], u1[1])); w.w = cvt_pk_bf16(silu_mul(g1[2], u1[2]), silu_mul(g1[3], u1[3]));
;                 __builtin_nontemporal_store(w, (u32x4*)(O + (size_t)row * ldc + col0)); }
; template <class Epi, class Sched, bool ALIGN_EPI = false, bool SP2 = false>
; __device__ __forceinline__ void gemm_phase(PG8_LAS unsigned char* lds, const Gemm g, const Sched& S, const Epi& E) {
;     ...
;         if constexpr (!Epi::AFTER_DRAIN) { E(acc, cur, wr, wc, fr, fq); S.done(cur); }
;         if (!has_next) break;
	v_add_f32_e32 v49, 1.0, v40
	v_add_f32_e32 v52, 1.0, v41
	v_rcp_f32_e32 v40, v42
	v_rcp_f32_e32 v41, v43
	v_rcp_f32_e32 v42, v44
	v_rcp_f32_e32 v43, v45
	v_rcp_f32_e32 v44, v46
	v_rcp_f32_e32 v45, v47
	v_rcp_f32_e32 v46, v49
	v_rcp_f32_e32 v47, v52
	v_pk_mul_f32 v[36:37], v[36:37], v[40:41]
	v_pk_mul_f32 v[38:39], v[38:39], v[42:43]
	v_pk_mul_f32 v[40:41], v[32:33], v[44:45]
	v_pk_mul_f32 v[42:43], v[34:35], v[46:47]
	v_cvt_pk_bf16_f32 v32, v36, v37
	v_cvt_pk_bf16_f32 v33, v38, v39
	v_cvt_pk_bf16_f32 v34, v40, v41
	v_cvt_pk_bf16_f32 v35, v42, v43
	global_store_dwordx4 v[50:51], v[32:35], off nt
	s_nop 1
	v_mad_i64_i32 v[34:35], s[0:1], v48, s56, v[146:147]
	v_lshl_add_u64 v[34:35], v[34:35], 0, v[148:149]
	v_add_u32_e32 v32, 0xb0, v150
	v_ashrrev_i32_e32 v33, 31, v32
	v_lshlrev_b64 v[38:39], 6, v[32:33]
	v_lshl_add_u64 v[38:39], v[136:137], 0, v[38:39]
	v_mov_b32_e32 v36, v196
	v_pk_mul_f32 v[30:31], v[30:31], v[36:37] op_sel_hi:[1,0]
	v_pk_mul_f32 v[28:29], v[28:29], v[36:37] op_sel_hi:[1,0]
	v_pk_mul_f32 v[26:27], v[26:27], v[36:37] op_sel_hi:[1,0]
	v_pk_mul_f32 v[24:25], v[24:25], v[36:37] op_sel_hi:[1,0]
	v_pk_mul_f32 v[20:21], v[20:21], v[36:37] op_sel_hi:[1,0]
	v_pk_mul_f32 v[22:23], v[22:23], v[36:37] op_sel_hi:[1,0]
	v_pk_mul_f32 v[16:17], v[16:17], v[36:37] op_sel_hi:[1,0]
	v_pk_mul_f32 v[18:19], v[18:19], v[36:37] op_sel_hi:[1,0]
	v_mul_f32_e32 v33, 0xbfb8aa3b, v28
	v_mul_f32_e32 v36, 0xbfb8aa3b, v29
	v_pk_mul_f32 v[22:23], v[30:31], v[22:23]
	v_pk_mul_f32 v[20:21], v[28:29], v[20:21]
	v_mul_f32_e32 v28, 0xbfb8aa3b, v30
	v_mul_f32_e32 v29, 0xbfb8aa3b, v31
	v_mul_f32_e32 v30, 0xbfb8aa3b, v24
	v_mul_f32_e32 v31, 0xbfb8aa3b, v25
	v_pk_mul_f32 v[16:17], v[24:25], v[16:17]
	v_mul_f32_e32 v24, 0xbfb8aa3b, v26
	v_mul_f32_e32 v25, 0xbfb8aa3b, v27
	v_pk_mul_f32 v[18:19], v[26:27], v[18:19]
	v_exp_f32_e32 v26, v33
	v_exp_f32_e32 v27, v36
	v_exp_f32_e32 v28, v28
	v_exp_f32_e32 v29, v29
	v_exp_f32_e32 v30, v30
	v_exp_f32_e32 v31, v31
	v_exp_f32_e32 v24, v24
	v_exp_f32_e32 v25, v25
	v_add_f32_e32 v26, 1.0, v26
	v_add_f32_e32 v27, 1.0, v27
	v_add_f32_e32 v28, 1.0, v28
	v_add_f32_e32 v29, 1.0, v29
	v_add_f32_e32 v30, 1.0, v30
	v_add_f32_e32 v31, 1.0, v31
	v_add_f32_e32 v33, 1.0, v24
	v_add_f32_e32 v36, 1.0, v25
	v_rcp_f32_e32 v24, v26
	v_rcp_f32_e32 v25, v27
	v_rcp_f32_e32 v26, v28
	v_rcp_f32_e32 v27, v29
	v_rcp_f32_e32 v28, v30
	v_rcp_f32_e32 v29, v31
	v_rcp_f32_e32 v30, v33
	v_rcp_f32_e32 v31, v36
	v_pk_mul_f32 v[20:21], v[20:21], v[24:25]
	v_pk_mul_f32 v[22:23], v[22:23], v[26:27]
	v_pk_mul_f32 v[24:25], v[16:17], v[28:29]
	v_pk_mul_f32 v[26:27], v[18:19], v[30:31]
	v_cvt_pk_bf16_f32 v16, v20, v21
	v_cvt_pk_bf16_f32 v17, v22, v23
	v_cvt_pk_bf16_f32 v18, v24, v25
	v_cvt_pk_bf16_f32 v19, v26, v27
	global_store_dwordx4 v[34:35], v[16:19], off nt
	s_nop 1
	v_mad_i64_i32 v[18:19], s[0:1], v32, s56, v[146:147]
	v_lshl_add_u64 v[18:19], v[18:19], 0, v[148:149]
	s_mov_b64 s[0:1], -1
	v_mov_b32_e32 v16, v200
	v_pk_mul_f32 v[14:15], v[14:15], v[16:17] op_sel_hi:[1,0]
	v_pk_mul_f32 v[12:13], v[12:13], v[16:17] op_sel_hi:[1,0]
	v_pk_mul_f32 v[10:11], v[10:11], v[16:17] op_sel_hi:[1,0]
	v_pk_mul_f32 v[8:9], v[8:9], v[16:17] op_sel_hi:[1,0]
	v_pk_mul_f32 v[4:5], v[4:5], v[16:17] op_sel_hi:[1,0]
	v_pk_mul_f32 v[6:7], v[6:7], v[16:17] op_sel_hi:[1,0]
	v_pk_mul_f32 v[0:1], v[0:1], v[16:17] op_sel_hi:[1,0]
	v_pk_mul_f32 v[2:3], v[2:3], v[16:17] op_sel_hi:[1,0]
	v_mul_f32_e32 v16, 0xbfb8aa3b, v12
	v_mul_f32_e32 v17, 0xbfb8aa3b, v13
	v_pk_mul_f32 v[6:7], v[14:15], v[6:7]
	v_pk_mul_f32 v[4:5], v[12:13], v[4:5]
	v_mul_f32_e32 v12, 0xbfb8aa3b, v14
	v_mul_f32_e32 v13, 0xbfb8aa3b, v15
	v_mul_f32_e32 v14, 0xbfb8aa3b, v8
	v_mul_f32_e32 v15, 0xbfb8aa3b, v9
	v_pk_mul_f32 v[0:1], v[8:9], v[0:1]
	v_mul_f32_e32 v8, 0xbfb8aa3b, v10
	v_mul_f32_e32 v9, 0xbfb8aa3b, v11
	v_pk_mul_f32 v[2:3], v[10:11], v[2:3]
	v_exp_f32_e32 v10, v16
	v_exp_f32_e32 v11, v17
	v_exp_f32_e32 v12, v12
	v_exp_f32_e32 v13, v13
	v_exp_f32_e32 v14, v14
	v_exp_f32_e32 v15, v15
	v_exp_f32_e32 v8, v8
	v_exp_f32_e32 v9, v9
	v_add_f32_e32 v10, 1.0, v10
	v_add_f32_e32 v11, 1.0, v11
	v_add_f32_e32 v12, 1.0, v12
	v_add_f32_e32 v13, 1.0, v13
	v_add_f32_e32 v14, 1.0, v14
	v_add_f32_e32 v15, 1.0, v15
	v_add_f32_e32 v16, 1.0, v8
	v_add_f32_e32 v17, 1.0, v9
	v_rcp_f32_e32 v8, v10
	v_rcp_f32_e32 v9, v11
	v_rcp_f32_e32 v10, v12
	v_rcp_f32_e32 v11, v13
	v_rcp_f32_e32 v12, v14
	v_rcp_f32_e32 v13, v15
	v_rcp_f32_e32 v14, v16
	v_rcp_f32_e32 v15, v17
	v_pk_mul_f32 v[4:5], v[4:5], v[8:9]
	v_pk_mul_f32 v[6:7], v[6:7], v[10:11]
	v_pk_mul_f32 v[8:9], v[0:1], v[12:13]
	v_pk_mul_f32 v[10:11], v[2:3], v[14:15]
	v_cvt_pk_bf16_f32 v0, v4, v5
	v_cvt_pk_bf16_f32 v1, v6, v7
	v_cvt_pk_bf16_f32 v2, v8, v9
	v_cvt_pk_bf16_f32 v3, v10, v11
	global_store_dwordx4 v[18:19], v[0:3], off nt
	s_cbranch_vccnz .LBB0_668
	s_andn2_b64 vcc, exec, s[6:7]
	s_cbranch_vccnz .LBB0_667
	s_barrier
	s_branch .LBB0_667

; __device__ __forceinline__ unsigned cvt_pk_bf16(float lo, float hi) { const cvt_f32x2_t v = {lo, hi}; const cvt_bf16x2_t b = __builtin_convertvector(v, cvt_bf16x2_t); return __builtin_bit_cast(unsigned, b); }
; __device__ __forceinline__ float silu_mul(float g, float u) { return g * u * __builtin_amdgcn_rcpf(1.0f + __builtin_amdgcn_exp2f(g * -1.4426950408889634f)); }
; __device__ __forceinline__ float rstd_from_slots(const float* slots, int row, int fq) {
;     const f32x4 s4 = *(const f32x4*)(slots + (size_t)row * 16 + 4 * fq);
;     float s = (s4[0] + s4[1]) + (s4[2] + s4[3]);
;     s += __shfl_xor(s, 16); s += __shfl_xor(s, 32);
;     return __builtin_amdgcn_rsqf(s * (1.0f / 1024.0f) + RMS_EPS_F);
; }
;     __device__ __forceinline__ void operator()(const f32x4 (&acc)[2][2][4][2], const Unit& u, int wr, int wc, int fr, int fq) const {
;         const int row0 = u.pm * BM + wr * 64 + fr; const int col0 = u.pn * HALF + wc * 32 + 8 * fq;
; #pragma unroll
;         for (int ai = 0; ai < 2; ++ai)
; #pragma unroll
;             for (int m = 0; m < 4; ++m) { const int row = row0 + ai * HALF + m * 16;
;                 const float sc = rstd_from_slots(slots, row, fq);
;                 const f32x4 g0 = acc[ai][0][m][0] * sc, g1 = acc[ai][0][m][1] * sc, u0 = acc[ai][1][m][0] * sc, u1 = acc[ai][1][m][1] * sc;
;                 u32x4 w; w.x = cvt_pk_bf16(silu_mul(g0[0], u0[0]), silu_mul(g0[1], u0[1])); w.y = cvt_pk_bf16(silu_mul(g0[2], u0[2]), silu_mul(g0[3], u0[3]));
;                 w.z = cvt_pk_bf16(silu_mul(g1[0], u1[0]), silu_mul(g1[1], u1[1])); w.w = cvt_pk_bf16(silu_mul(g1[2], u1[2]), silu_mul(g1[3], u1[3]));
;                 __builtin_nontemporal_store(w, (u32x4*)(O + (size_t)row * ldc + col0)); }
.LBB0_1114:
	v_xor_b32_e32 v216, 16, v160
	v_xor_b32_e32 v217, 32, v160
	v_lshlrev_b32_e32 v216, 2, v216
	v_lshlrev_b32_e32 v217, 2, v217
	s_waitcnt vmcnt(0)
	v_add_f32_e32 v172, v172, v173
	v_add_f32_e32 v173, v175, v174
	v_add_f32_e32 v176, v176, v177
	v_add_f32_e32 v177, v179, v178
	v_add_f32_e32 v180, v180, v181
	v_add_f32_e32 v181, v183, v182
	v_add_f32_e32 v184, v184, v185
	v_add_f32_e32 v185, v187, v186
	v_add_f32_e32 v188, v188, v189
	v_add_f32_e32 v189, v191, v190
	v_add_f32_e32 v192, v192, v193
	v_add_f32_e32 v193, v195, v194
	v_add_f32_e32 v196, v196, v197
	v_add_f32_e32 v197, v199, v198
	v_add_f32_e32 v200, v200, v201
	v_add_f32_e32 v201, v203, v202
	v_add_f32_e32 v172, v172, v173
	v_add_f32_e32 v176, v176, v177
	v_add_f32_e32 v180, v180, v181
	v_add_f32_e32 v184, v184, v185
	v_add_f32_e32 v188, v188, v189
	v_add_f32_e32 v192, v192, v193
	v_add_f32_e32 v196, v196, v197
	v_add_f32_e32 v200, v200, v201
	ds_bpermute_b32 v173, v216, v172
	ds_bpermute_b32 v177, v216, v176
	ds_bpermute_b32 v181, v216, v180
	ds_bpermute_b32 v185, v216, v184
	ds_bpermute_b32 v189, v216, v188
	ds_bpermute_b32 v193, v216, v192
	ds_bpermute_b32 v197, v216, v196
	ds_bpermute_b32 v201, v216, v200
	s_waitcnt lgkmcnt(0)
	v_add_f32_e32 v172, v172, v173
	v_add_f32_e32 v176, v176, v177
	v_add_f32_e32 v180, v180, v181
	v_add_f32_e32 v184, v184, v185
	v_add_f32_e32 v188, v188, v189
	v_add_f32_e32 v192, v192, v193
	v_add_f32_e32 v196, v196, v197
	v_add_f32_e32 v200, v200, v201
	ds_bpermute_b32 v173, v217, v172
	ds_bpermute_b32 v177, v217, v176
	ds_bpermute_b32 v181, v217, v180
	ds_bpermute_b32 v185, v217, v184
	ds_bpermute_b32 v189, v217, v188
	ds_bpermute_b32 v193, v217, v192
	ds_bpermute_b32 v197, v217, v196
	ds_bpermute_b32 v201, v217, v200
	s_waitcnt lgkmcnt(0)
	v_add_f32_e32 v172, v172, v173
	v_add_f32_e32 v176, v176, v177
	v_add_f32_e32 v180, v180, v181
	v_add_f32_e32 v184, v184, v185
	v_add_f32_e32 v188, v188, v189
	v_add_f32_e32 v192, v192, v193
	v_add_f32_e32 v196, v196, v197
	v_add_f32_e32 v200, v200, v201
	v_fmamk_f32 v172, v172, 0x3a800000, v161
	v_fmamk_f32 v176, v176, 0x3a800000, v161
	v_fmamk_f32 v180, v180, 0x3a800000, v161
	v_fmamk_f32 v184, v184, 0x3a800000, v161
	v_fmamk_f32 v188, v188, 0x3a800000, v161
	v_fmamk_f32 v192, v192, 0x3a800000, v161
	v_fmamk_f32 v196, v196, 0x3a800000, v161
	v_fmamk_f32 v200, v200, 0x3a800000, v161
	v_rsq_f32_e32 v172, v172
	v_rsq_f32_e32 v176, v176
	v_rsq_f32_e32 v180, v180
	v_rsq_f32_e32 v184, v184
	v_rsq_f32_e32 v188, v188
	v_rsq_f32_e32 v192, v192
	v_rsq_f32_e32 v196, v196
	v_rsq_f32_e32 v200, v200
	v_lshl_add_u32 v150, s0, 8, v152
	v_ashrrev_i32_e32 v151, 31, v150
	v_lshlrev_b64 v[146:147], 6, v[150:151]
	v_lshl_add_u64 v[146:147], v[136:137], 0, v[146:147]
	v_and_b32_e32 v151, 64, v160
	v_xor_b32_e32 v149, 16, v160
	v_add_u32_e32 v169, 64, v151
	v_cmp_lt_i32_e32 vcc, v149, v169
	v_xor_b32_e32 v168, 32, v160
	v_lshl_or_b32 v148, s1, 7, v156
	v_cndmask_b32_e32 v149, v160, v149, vcc
	v_lshlrev_b32_e32 v151, 2, v149
	v_cmp_lt_i32_e32 vcc, v168, v169
	v_mov_b64_e32 v[146:147], s[10:11]
	v_ashrrev_i32_e32 v149, 31, v148
	v_lshlrev_b64 v[148:149], 1, v[148:149]
	v_or_b32_e32 v166, 16, v150
	v_cndmask_b32_e32 v162, v160, v168, vcc
	v_lshlrev_b32_e32 v162, 2, v162
	v_ashrrev_i32_e32 v167, 31, v166
	v_lshlrev_b64 v[170:171], 6, v[166:167]
	v_mad_i64_i32 v[164:165], s[0:1], v150, s56, v[146:147]
	v_lshl_add_u64 v[164:165], v[164:165], 0, v[148:149]
	v_lshl_add_u64 v[170:171], v[136:137], 0, v[170:171]
	s_andn2_b64 vcc, exec, s[2:3]
	v_mov_b32_e32 v168, v172
	v_pk_mul_f32 v[126:127], v[126:127], v[168:169] op_sel_hi:[1,0]
	v_pk_mul_f32 v[124:125], v[124:125], v[168:169] op_sel_hi:[1,0]
	v_pk_mul_f32 v[122:123], v[122:123], v[168:169] op_sel_hi:[1,0]
	v_pk_mul_f32 v[120:121], v[120:121], v[168:169] op_sel_hi:[1,0]
	v_pk_mul_f32 v[116:117], v[116:117], v[168:169] op_sel_hi:[1,0]
	v_pk_mul_f32 v[118:119], v[118:119], v[168:169] op_sel_hi:[1,0]
	v_pk_mul_f32 v[112:113], v[112:113], v[168:169] op_sel_hi:[1,0]
	v_pk_mul_f32 v[114:115], v[114:115], v[168:169] op_sel_hi:[1,0]
	v_mul_f32_e32 v163, 0xbfb8aa3b, v124
	v_mul_f32_e32 v167, 0xbfb8aa3b, v125
	v_pk_mul_f32 v[118:119], v[126:127], v[118:119]
	v_pk_mul_f32 v[116:117], v[124:125], v[116:117]
	v_mul_f32_e32 v124, 0xbfb8aa3b, v126
	v_mul_f32_e32 v125, 0xbfb8aa3b, v127
	v_mul_f32_e32 v126, 0xbfb8aa3b, v120
	v_mul_f32_e32 v127, 0xbfb8aa3b, v121
	v_pk_mul_f32 v[112:113], v[120:121], v[112:113]
	v_mul_f32_e32 v120, 0xbfb8aa3b, v122
	v_mul_f32_e32 v121, 0xbfb8aa3b, v123
	v_pk_mul_f32 v[114:115], v[122:123], v[114:115]
	v_exp_f32_e32 v122, v163
	v_exp_f32_e32 v123, v167
	v_exp_f32_e32 v124, v124
	v_exp_f32_e32 v125, v125
	v_exp_f32_e32 v126, v126
	v_exp_f32_e32 v127, v127
	v_exp_f32_e32 v120, v120
	v_exp_f32_e32 v121, v121
	v_add_f32_e32 v122, 1.0, v122
	v_add_f32_e32 v123, 1.0, v123
	v_add_f32_e32 v124, 1.0, v124
	v_add_f32_e32 v125, 1.0, v125
	v_add_f32_e32 v126, 1.0, v126
	v_add_f32_e32 v127, 1.0, v127
	v_add_f32_e32 v163, 1.0, v120
	v_add_f32_e32 v167, 1.0, v121
	v_rcp_f32_e32 v120, v122
	v_rcp_f32_e32 v121, v123
	v_rcp_f32_e32 v122, v124
	v_rcp_f32_e32 v123, v125
	v_rcp_f32_e32 v124, v126
	v_rcp_f32_e32 v125, v127
	v_rcp_f32_e32 v126, v163
	v_rcp_f32_e32 v127, v167
	v_pk_mul_f32 v[116:117], v[116:117], v[120:121]
	v_pk_mul_f32 v[118:119], v[118:119], v[122:123]
	v_pk_mul_f32 v[120:121], v[112:113], v[124:125]
	v_pk_mul_f32 v[122:123], v[114:115], v[126:127]
	v_cvt_pk_bf16_f32 v112, v116, v117
	v_cvt_pk_bf16_f32 v113, v118, v119
	v_cvt_pk_bf16_f32 v114, v120, v121
	v_cvt_pk_bf16_f32 v115, v122, v123
	global_store_dwordx4 v[164:165], v[112:115], off nt
	s_nop 1
; __device__ __forceinline__ unsigned cvt_pk_bf16(float lo, float hi) { const cvt_f32x2_t v = {lo, hi}; const cvt_bf16x2_t b = __builtin_convertvector(v, cvt_bf16x2_t); return __builtin_bit_cast(unsigned, b); }
; __device__ __forceinline__ float silu_mul(float g, float u) { return g * u * __builtin_amdgcn_rcpf(1.0f + __builtin_amdgcn_exp2f(g * -1.4426950408889634f)); }
; __device__ __forceinline__ float rstd_from_slots(const float* slots, int row, int fq) {
;     const f32x4 s4 = *(const f32x4*)(slots + (size_t)row * 16 + 4 * fq);
;     float s = (s4[0] + s4[1]) + (s4[2] + s4[3]);
;     s += __shfl_xor(s, 16); s += __shfl_xor(s, 32);
;     return __builtin_amdgcn_rsqf(s * (1.0f / 1024.0f) + RMS_EPS_F);
;     __device__ __forceinline__ void operator()(const f32x4 (&acc)[2][2][4][2], const Unit& u, int wr, int wc, int fr, int fq) const {
;     ...
;             for (int m = 0; m < 4; ++m) { const int row = row0 + ai * HALF + m * 16;
;                 const float sc = rstd_from_slots(slots, row, fq);
;                 const f32x4 g0 = acc[ai][0][m][0] * sc, g1 = acc[ai][0][m][1] * sc, u0 = acc[ai][1][m][0] * sc, u1 = acc[ai][1][m][1] * sc;
;                 u32x4 w; w.x = cvt_pk_bf16(silu_mul(g0[0], u0[0]), silu_mul(g0[1], u0[1])); w.y = cvt_pk_bf16(silu_mul(g0[2], u0[2]), silu_mul(g0[3], u0[3]));
;                 w.z = cvt_pk_bf16(silu_mul(g1[0], u1[0]), silu_mul(g1[1], u1[1])); w.w = cvt_pk_bf16(silu_mul(g1[2], u1[2]), silu_mul(g1[3], u1[3]));
;                 __builtin_nontemporal_store(w, (u32x4*)(O + (size_t)row * ldc + col0)); }
	v_mad_i64_i32 v[114:115], s[0:1], v166, s56, v[146:147]
	v_lshl_add_u64 v[114:115], v[114:115], 0, v[148:149]
	v_or_b32_e32 v112, 32, v150
	v_ashrrev_i32_e32 v113, 31, v112
	v_lshlrev_b64 v[118:119], 6, v[112:113]
	v_lshl_add_u64 v[118:119], v[136:137], 0, v[118:119]
	v_mov_b32_e32 v116, v176
	v_pk_mul_f32 v[110:111], v[110:111], v[116:117] op_sel_hi:[1,0]
	v_pk_mul_f32 v[108:109], v[108:109], v[116:117] op_sel_hi:[1,0]
	v_pk_mul_f32 v[106:107], v[106:107], v[116:117] op_sel_hi:[1,0]
	v_pk_mul_f32 v[104:105], v[104:105], v[116:117] op_sel_hi:[1,0]
	v_pk_mul_f32 v[100:101], v[100:101], v[116:117] op_sel_hi:[1,0]
	v_pk_mul_f32 v[102:103], v[102:103], v[116:117] op_sel_hi:[1,0]
	v_pk_mul_f32 v[96:97], v[96:97], v[116:117] op_sel_hi:[1,0]
	v_pk_mul_f32 v[98:99], v[98:99], v[116:117] op_sel_hi:[1,0]
	v_mul_f32_e32 v113, 0xbfb8aa3b, v108
	v_mul_f32_e32 v116, 0xbfb8aa3b, v109
	v_pk_mul_f32 v[102:103], v[110:111], v[102:103]
	v_pk_mul_f32 v[100:101], v[108:109], v[100:101]
	v_mul_f32_e32 v108, 0xbfb8aa3b, v110
	v_mul_f32_e32 v109, 0xbfb8aa3b, v111
	v_mul_f32_e32 v110, 0xbfb8aa3b, v104
	v_mul_f32_e32 v111, 0xbfb8aa3b, v105
	v_pk_mul_f32 v[96:97], v[104:105], v[96:97]
	v_mul_f32_e32 v104, 0xbfb8aa3b, v106
	v_mul_f32_e32 v105, 0xbfb8aa3b, v107
	v_pk_mul_f32 v[98:99], v[106:107], v[98:99]
	v_exp_f32_e32 v106, v113
	v_exp_f32_e32 v107, v116
	v_exp_f32_e32 v108, v108
	v_exp_f32_e32 v109, v109
	v_exp_f32_e32 v110, v110
	v_exp_f32_e32 v111, v111
	v_exp_f32_e32 v104, v104
	v_exp_f32_e32 v105, v105
	v_add_f32_e32 v106, 1.0, v106
	v_add_f32_e32 v107, 1.0, v107
	v_add_f32_e32 v108, 1.0, v108
	v_add_f32_e32 v109, 1.0, v109
	v_add_f32_e32 v110, 1.0, v110
	v_add_f32_e32 v111, 1.0, v111
	v_add_f32_e32 v113, 1.0, v104
	v_add_f32_e32 v116, 1.0, v105
	v_rcp_f32_e32 v104, v106
	v_rcp_f32_e32 v105, v107
	v_rcp_f32_e32 v106, v108
	v_rcp_f32_e32 v107, v109
	v_rcp_f32_e32 v108, v110
	v_rcp_f32_e32 v109, v111
	v_rcp_f32_e32 v110, v113
	v_rcp_f32_e32 v111, v116
	v_pk_mul_f32 v[100:101], v[100:101], v[104:105]
	v_pk_mul_f32 v[102:103], v[102:103], v[106:107]
	v_pk_mul_f32 v[104:105], v[96:97], v[108:109]
	v_pk_mul_f32 v[106:107], v[98:99], v[110:111]
	v_cvt_pk_bf16_f32 v96, v100, v101
	v_cvt_pk_bf16_f32 v97, v102, v103
	v_cvt_pk_bf16_f32 v98, v104, v105
	v_cvt_pk_bf16_f32 v99, v106, v107
	global_store_dwordx4 v[114:115], v[96:99], off nt
	s_nop 1
	v_mad_i64_i32 v[98:99], s[0:1], v112, s56, v[146:147]
	v_lshl_add_u64 v[98:99], v[98:99], 0, v[148:149]
	v_or_b32_e32 v96, 48, v150
	v_ashrrev_i32_e32 v97, 31, v96
	v_lshlrev_b64 v[102:103], 6, v[96:97]
	v_lshl_add_u64 v[102:103], v[136:137], 0, v[102:103]
	v_mov_b32_e32 v100, v180
	v_pk_mul_f32 v[94:95], v[94:95], v[100:101] op_sel_hi:[1,0]
	v_pk_mul_f32 v[92:93], v[92:93], v[100:101] op_sel_hi:[1,0]
	v_pk_mul_f32 v[90:91], v[90:91], v[100:101] op_sel_hi:[1,0]
	v_pk_mul_f32 v[88:89], v[88:89], v[100:101] op_sel_hi:[1,0]
	v_pk_mul_f32 v[84:85], v[84:85], v[100:101] op_sel_hi:[1,0]
	v_pk_mul_f32 v[86:87], v[86:87], v[100:101] op_sel_hi:[1,0]
	v_pk_mul_f32 v[80:81], v[80:81], v[100:101] op_sel_hi:[1,0]
	v_pk_mul_f32 v[82:83], v[82:83], v[100:101] op_sel_hi:[1,0]
	v_mul_f32_e32 v97, 0xbfb8aa3b, v92
	v_mul_f32_e32 v100, 0xbfb8aa3b, v93
	v_pk_mul_f32 v[86:87], v[94:95], v[86:87]
	v_pk_mul_f32 v[84:85], v[92:93], v[84:85]
	v_mul_f32_e32 v92, 0xbfb8aa3b, v94
	v_mul_f32_e32 v93, 0xbfb8aa3b, v95
	v_mul_f32_e32 v94, 0xbfb8aa3b, v88
	v_mul_f32_e32 v95, 0xbfb8aa3b, v89
	v_pk_mul_f32 v[80:81], v[88:89], v[80:81]
	v_mul_f32_e32 v88, 0xbfb8aa3b, v90
	v_mul_f32_e32 v89, 0xbfb8aa3b, v91
	v_pk_mul_f32 v[82:83], v[90:91], v[82:83]
	v_exp_f32_e32 v90, v97
	v_exp_f32_e32 v91, v100
	v_exp_f32_e32 v92, v92
	v_exp_f32_e32 v93, v93
	v_exp_f32_e32 v94, v94
	v_exp_f32_e32 v95, v95
	v_exp_f32_e32 v88, v88
	v_exp_f32_e32 v89, v89
	v_add_f32_e32 v90, 1.0, v90
	v_add_f32_e32 v91, 1.0, v91
	v_add_f32_e32 v92, 1.0, v92
	v_add_f32_e32 v93, 1.0, v93
	v_add_f32_e32 v94, 1.0, v94
	v_add_f32_e32 v95, 1.0, v95
	v_add_f32_e32 v97, 1.0, v88
	v_add_f32_e32 v100, 1.0, v89
	v_rcp_f32_e32 v88, v90
	v_rcp_f32_e32 v89, v91
	v_rcp_f32_e32 v90, v92
	v_rcp_f32_e32 v91, v93
	v_rcp_f32_e32 v92, v94
	v_rcp_f32_e32 v93, v95
	v_rcp_f32_e32 v94, v97
	v_rcp_f32_e32 v95, v100
	v_pk_mul_f32 v[84:85], v[84:85], v[88:89]
	v_pk_mul_f32 v[86:87], v[86:87], v[90:91]
	v_pk_mul_f32 v[88:89], v[80:81], v[92:93]
	v_pk_mul_f32 v[90:91], v[82:83], v[94:95]
	v_cvt_pk_bf16_f32 v80, v84, v85
	v_cvt_pk_bf16_f32 v81, v86, v87
	v_cvt_pk_bf16_f32 v82, v88, v89
	v_cvt_pk_bf16_f32 v83, v90, v91
	global_store_dwordx4 v[98:99], v[80:83], off nt
	s_nop 1
	v_mad_i64_i32 v[82:83], s[0:1], v96, s56, v[146:147]
	v_lshl_add_u64 v[82:83], v[82:83], 0, v[148:149]
	v_add_u32_e32 v80, 0x80, v150
	v_ashrrev_i32_e32 v81, 31, v80
	v_lshlrev_b64 v[86:87], 6, v[80:81]
	v_lshl_add_u64 v[86:87], v[136:137], 0, v[86:87]
	v_mov_b32_e32 v84, v184
	v_pk_mul_f32 v[78:79], v[78:79], v[84:85] op_sel_hi:[1,0]
	v_pk_mul_f32 v[76:77], v[76:77], v[84:85] op_sel_hi:[1,0]
	v_pk_mul_f32 v[74:75], v[74:75], v[84:85] op_sel_hi:[1,0]
	v_pk_mul_f32 v[72:73], v[72:73], v[84:85] op_sel_hi:[1,0]
	v_pk_mul_f32 v[68:69], v[68:69], v[84:85] op_sel_hi:[1,0]
	v_pk_mul_f32 v[70:71], v[70:71], v[84:85] op_sel_hi:[1,0]
	v_pk_mul_f32 v[64:65], v[64:65], v[84:85] op_sel_hi:[1,0]
	v_pk_mul_f32 v[66:67], v[66:67], v[84:85] op_sel_hi:[1,0]
	v_mul_f32_e32 v81, 0xbfb8aa3b, v76
	v_mul_f32_e32 v84, 0xbfb8aa3b, v77
	v_pk_mul_f32 v[70:71], v[78:79], v[70:71]
	v_pk_mul_f32 v[68:69], v[76:77], v[68:69]
	v_mul_f32_e32 v76, 0xbfb8aa3b, v78
	v_mul_f32_e32 v77, 0xbfb8aa3b, v79
	v_mul_f32_e32 v78, 0xbfb8aa3b, v72
	v_mul_f32_e32 v79, 0xbfb8aa3b, v73
; __device__ __forceinline__ unsigned cvt_pk_bf16(float lo, float hi) { const cvt_f32x2_t v = {lo, hi}; const cvt_bf16x2_t b = __builtin_convertvector(v, cvt_bf16x2_t); return __builtin_bit_cast(unsigned, b); }
; __device__ __forceinline__ float silu_mul(float g, float u) { return g * u * __builtin_amdgcn_rcpf(1.0f + __builtin_amdgcn_exp2f(g * -1.4426950408889634f)); }
; __device__ __forceinline__ float rstd_from_slots(const float* slots, int row, int fq) {
;     const f32x4 s4 = *(const f32x4*)(slots + (size_t)row * 16 + 4 * fq);
;     float s = (s4[0] + s4[1]) + (s4[2] + s4[3]);
;     s += __shfl_xor(s, 16); s += __shfl_xor(s, 32);
;     return __builtin_amdgcn_rsqf(s * (1.0f / 1024.0f) + RMS_EPS_F);
;     __device__ __forceinline__ void operator()(const f32x4 (&acc)[2][2][4][2], const Unit& u, int wr, int wc, int fr, int fq) const {
;     ...
;             for (int m = 0; m < 4; ++m) { const int row = row0 + ai * HALF + m * 16;
;                 const float sc = rstd_from_slots(slots, row, fq);
;                 const f32x4 g0 = acc[ai][0][m][0] * sc, g1 = acc[ai][0][m][1] * sc, u0 = acc[ai][1][m][0] * sc, u1 = acc[ai][1][m][1] * sc;
;                 u32x4 w; w.x = cvt_pk_bf16(silu_mul(g0[0], u0[0]), silu_mul(g0[1], u0[1])); w.y = cvt_pk_bf16(silu_mul(g0[2], u0[2]), silu_mul(g0[3], u0[3]));
;                 w.z = cvt_pk_bf16(silu_mul(g1[0], u1[0]), silu_mul(g1[1], u1[1])); w.w = cvt_pk_bf16(silu_mul(g1[2], u1[2]), silu_mul(g1[3], u1[3]));
;                 __builtin_nontemporal_store(w, (u32x4*)(O + (size_t)row * ldc + col0)); }
	v_pk_mul_f32 v[64:65], v[72:73], v[64:65]
	v_mul_f32_e32 v72, 0xbfb8aa3b, v74
	v_mul_f32_e32 v73, 0xbfb8aa3b, v75
	v_pk_mul_f32 v[66:67], v[74:75], v[66:67]
	v_exp_f32_e32 v74, v81
	v_exp_f32_e32 v75, v84
	v_exp_f32_e32 v76, v76
	v_exp_f32_e32 v77, v77
	v_exp_f32_e32 v78, v78
	v_exp_f32_e32 v79, v79
	v_exp_f32_e32 v72, v72
	v_exp_f32_e32 v73, v73
	v_add_f32_e32 v74, 1.0, v74
	v_add_f32_e32 v75, 1.0, v75
	v_add_f32_e32 v76, 1.0, v76
	v_add_f32_e32 v77, 1.0, v77
	v_add_f32_e32 v78, 1.0, v78
	v_add_f32_e32 v79, 1.0, v79
	v_add_f32_e32 v81, 1.0, v72
	v_add_f32_e32 v84, 1.0, v73
	v_rcp_f32_e32 v72, v74
	v_rcp_f32_e32 v73, v75
	v_rcp_f32_e32 v74, v76
	v_rcp_f32_e32 v75, v77
	v_rcp_f32_e32 v76, v78
	v_rcp_f32_e32 v77, v79
	v_rcp_f32_e32 v78, v81
	v_rcp_f32_e32 v79, v84
	v_pk_mul_f32 v[68:69], v[68:69], v[72:73]
	v_pk_mul_f32 v[70:71], v[70:71], v[74:75]
	v_pk_mul_f32 v[72:73], v[64:65], v[76:77]
	v_pk_mul_f32 v[74:75], v[66:67], v[78:79]
	v_cvt_pk_bf16_f32 v64, v68, v69
	v_cvt_pk_bf16_f32 v65, v70, v71
	v_cvt_pk_bf16_f32 v66, v72, v73
	v_cvt_pk_bf16_f32 v67, v74, v75
	global_store_dwordx4 v[82:83], v[64:67], off nt
	s_nop 1
	v_mad_i64_i32 v[66:67], s[0:1], v80, s56, v[146:147]
	v_lshl_add_u64 v[66:67], v[66:67], 0, v[148:149]
	v_add_u32_e32 v64, 0x90, v150
	v_ashrrev_i32_e32 v65, 31, v64
	v_lshlrev_b64 v[70:71], 6, v[64:65]
	v_lshl_add_u64 v[70:71], v[136:137], 0, v[70:71]
	v_mov_b32_e32 v68, v188
	v_pk_mul_f32 v[62:63], v[62:63], v[68:69] op_sel_hi:[1,0]
	v_pk_mul_f32 v[60:61], v[60:61], v[68:69] op_sel_hi:[1,0]
	v_pk_mul_f32 v[58:59], v[58:59], v[68:69] op_sel_hi:[1,0]
	v_pk_mul_f32 v[56:57], v[56:57], v[68:69] op_sel_hi:[1,0]
	v_pk_mul_f32 v[52:53], v[52:53], v[68:69] op_sel_hi:[1,0]
	v_pk_mul_f32 v[54:55], v[54:55], v[68:69] op_sel_hi:[1,0]
	v_pk_mul_f32 v[48:49], v[48:49], v[68:69] op_sel_hi:[1,0]
	v_pk_mul_f32 v[50:51], v[50:51], v[68:69] op_sel_hi:[1,0]
	v_mul_f32_e32 v65, 0xbfb8aa3b, v60
	v_mul_f32_e32 v68, 0xbfb8aa3b, v61
	v_pk_mul_f32 v[54:55], v[62:63], v[54:55]
	v_pk_mul_f32 v[52:53], v[60:61], v[52:53]
	v_mul_f32_e32 v60, 0xbfb8aa3b, v62
	v_mul_f32_e32 v61, 0xbfb8aa3b, v63
	v_mul_f32_e32 v62, 0xbfb8aa3b, v56
	v_mul_f32_e32 v63, 0xbfb8aa3b, v57
	v_pk_mul_f32 v[48:49], v[56:57], v[48:49]
	v_mul_f32_e32 v56, 0xbfb8aa3b, v58
	v_mul_f32_e32 v57, 0xbfb8aa3b, v59
	v_pk_mul_f32 v[50:51], v[58:59], v[50:51]
	v_exp_f32_e32 v58, v65
	v_exp_f32_e32 v59, v68
	v_exp_f32_e32 v60, v60
	v_exp_f32_e32 v61, v61
	v_exp_f32_e32 v62, v62
	v_exp_f32_e32 v63, v63
	v_exp_f32_e32 v56, v56
	v_exp_f32_e32 v57, v57
	v_add_f32_e32 v58, 1.0, v58
	v_add_f32_e32 v59, 1.0, v59
	v_add_f32_e32 v60, 1.0, v60
	v_add_f32_e32 v61, 1.0, v61
	v_add_f32_e32 v62, 1.0, v62
	v_add_f32_e32 v63, 1.0, v63
	v_add_f32_e32 v65, 1.0, v56
	v_add_f32_e32 v68, 1.0, v57
	v_rcp_f32_e32 v56, v58
	v_rcp_f32_e32 v57, v59
	v_rcp_f32_e32 v58, v60
	v_rcp_f32_e32 v59, v61
	v_rcp_f32_e32 v60, v62
	v_rcp_f32_e32 v61, v63
	v_rcp_f32_e32 v62, v65
	v_rcp_f32_e32 v63, v68
	v_pk_mul_f32 v[52:53], v[52:53], v[56:57]
	v_pk_mul_f32 v[54:55], v[54:55], v[58:59]
	v_pk_mul_f32 v[56:57], v[48:49], v[60:61]
	v_pk_mul_f32 v[58:59], v[50:51], v[62:63]
	v_cvt_pk_bf16_f32 v48, v52, v53
	v_cvt_pk_bf16_f32 v49, v54, v55
	v_cvt_pk_bf16_f32 v50, v56, v57
	v_cvt_pk_bf16_f32 v51, v58, v59
	global_store_dwordx4 v[66:67], v[48:51], off nt
	s_nop 1
	v_mad_i64_i32 v[50:51], s[0:1], v64, s56, v[146:147]
	v_lshl_add_u64 v[50:51], v[50:51], 0, v[148:149]
	v_add_u32_e32 v48, 0xa0, v150
	v_ashrrev_i32_e32 v49, 31, v48
	v_lshlrev_b64 v[54:55], 6, v[48:49]
	v_lshl_add_u64 v[54:55], v[136:137], 0, v[54:55]
	v_mov_b32_e32 v52, v192
	v_pk_mul_f32 v[46:47], v[46:47], v[52:53] op_sel_hi:[1,0]
	v_pk_mul_f32 v[44:45], v[44:45], v[52:53] op_sel_hi:[1,0]
	v_pk_mul_f32 v[42:43], v[42:43], v[52:53] op_sel_hi:[1,0]
	v_pk_mul_f32 v[40:41], v[40:41], v[52:53] op_sel_hi:[1,0]
	v_pk_mul_f32 v[36:37], v[36:37], v[52:53] op_sel_hi:[1,0]
	v_pk_mul_f32 v[38:39], v[38:39], v[52:53] op_sel_hi:[1,0]
	v_pk_mul_f32 v[32:33], v[32:33], v[52:53] op_sel_hi:[1,0]
	v_pk_mul_f32 v[34:35], v[34:35], v[52:53] op_sel_hi:[1,0]
	v_mul_f32_e32 v49, 0xbfb8aa3b, v44
	v_mul_f32_e32 v52, 0xbfb8aa3b, v45
	v_pk_mul_f32 v[38:39], v[46:47], v[38:39]
	v_pk_mul_f32 v[36:37], v[44:45], v[36:37]
	v_mul_f32_e32 v44, 0xbfb8aa3b, v46
	v_mul_f32_e32 v45, 0xbfb8aa3b, v47
	v_mul_f32_e32 v46, 0xbfb8aa3b, v40
	v_mul_f32_e32 v47, 0xbfb8aa3b, v41
	v_pk_mul_f32 v[32:33], v[40:41], v[32:33]
	v_mul_f32_e32 v40, 0xbfb8aa3b, v42
	v_mul_f32_e32 v41, 0xbfb8aa3b, v43
	v_pk_mul_f32 v[34:35], v[42:43], v[34:35]
	v_exp_f32_e32 v42, v49
	v_exp_f32_e32 v43, v52
	v_exp_f32_e32 v44, v44
	v_exp_f32_e32 v45, v45
	v_exp_f32_e32 v46, v46
	v_exp_f32_e32 v47, v47
	v_exp_f32_e32 v40, v40
	v_exp_f32_e32 v41, v41
	v_add_f32_e32 v42, 1.0, v42
	v_add_f32_e32 v43, 1.0, v43
	v_add_f32_e32 v44, 1.0, v44
	v_add_f32_e32 v45, 1.0, v45
	v_add_f32_e32 v46, 1.0, v46
	v_add_f32_e32 v47, 1.0, v47
; __device__ __forceinline__ unsigned cvt_pk_bf16(float lo, float hi) { const cvt_f32x2_t v = {lo, hi}; const cvt_bf16x2_t b = __builtin_convertvector(v, cvt_bf16x2_t); return __builtin_bit_cast(unsigned, b); }
; __device__ __forceinline__ float silu_mul(float g, float u) { return g * u * __builtin_amdgcn_rcpf(1.0f + __builtin_amdgcn_exp2f(g * -1.4426950408889634f)); }
; #define PG8_BAR __builtin_amdgcn_s_barrier()
;     __device__ __forceinline__ void operator()(const f32x4 (&acc)[2][2][4][2], const Unit& u, int wr, int wc, int fr, int fq) const {
;     ...
;             for (int m = 0; m < 4; ++m) { const int row = row0 + ai * HALF + m * 16;
;                 const float sc = rstd_from_slots(slots, row, fq);
;                 const f32x4 g0 = acc[ai][0][m][0] * sc, g1 = acc[ai][0][m][1] * sc, u0 = acc[ai][1][m][0] * sc, u1 = acc[ai][1][m][1] * sc;
;                 u32x4 w; w.x = cvt_pk_bf16(silu_mul(g0[0], u0[0]), silu_mul(g0[1], u0[1])); w.y = cvt_pk_bf16(silu_mul(g0[2], u0[2]), silu_mul(g0[3], u0[3]));
;                 w.z = cvt_pk_bf16(silu_mul(g1[0], u1[0]), silu_mul(g1[1], u1[1])); w.w = cvt_pk_bf16(silu_mul(g1[2], u1[2]), silu_mul(g1[3], u1[3]));
;                 __builtin_nontemporal_store(w, (u32x4*)(O + (size_t)row * ldc + col0)); }
; template <class Epi, class Sched, bool ALIGN_EPI = false, bool SP2 = false>
; __device__ __forceinline__ void gemm_phase(PG8_LAS unsigned char* lds, const Gemm g, const Sched& S, const Epi& E) {
;     ...
;         if constexpr (!Epi::AFTER_DRAIN) { E(acc, cur, wr, wc, fr, fq); S.done(cur); }
;         if (!has_next) break;
; #pragma unroll
;         for (int a = 0; a < 2; ++a)
; #pragma unroll
;             for (int b = 0; b < 2; ++b)
; #pragma unroll
;                 for (int m = 0; m < 4; ++m)
; #pragma unroll
;                     for (int n = 0; n < 2; ++n) acc[a][b][m][n] = (f32x4){0.f, 0.f, 0.f, 0.f};
;         cur = nxt; cA = nA; cB = nB; ++ui;
;         if constexpr (ALIGN_EPI) { if (wr == 1) PG8_BAR; }
	v_add_f32_e32 v49, 1.0, v40
	v_add_f32_e32 v52, 1.0, v41
	v_rcp_f32_e32 v40, v42
	v_rcp_f32_e32 v41, v43
	v_rcp_f32_e32 v42, v44
	v_rcp_f32_e32 v43, v45
	v_rcp_f32_e32 v44, v46
	v_rcp_f32_e32 v45, v47
	v_rcp_f32_e32 v46, v49
	v_rcp_f32_e32 v47, v52
	v_pk_mul_f32 v[36:37], v[36:37], v[40:41]
	v_pk_mul_f32 v[38:39], v[38:39], v[42:43]
	v_pk_mul_f32 v[40:41], v[32:33], v[44:45]
	v_pk_mul_f32 v[42:43], v[34:35], v[46:47]
	v_cvt_pk_bf16_f32 v32, v36, v37
	v_cvt_pk_bf16_f32 v33, v38, v39
	v_cvt_pk_bf16_f32 v34, v40, v41
	v_cvt_pk_bf16_f32 v35, v42, v43
	global_store_dwordx4 v[50:51], v[32:35], off nt
	s_nop 1
	v_mad_i64_i32 v[34:35], s[0:1], v48, s56, v[146:147]
	v_lshl_add_u64 v[34:35], v[34:35], 0, v[148:149]
	v_add_u32_e32 v32, 0xb0, v150
	v_ashrrev_i32_e32 v33, 31, v32
	v_lshlrev_b64 v[38:39], 6, v[32:33]
	v_lshl_add_u64 v[38:39], v[136:137], 0, v[38:39]
	v_mov_b32_e32 v36, v196
	v_pk_mul_f32 v[30:31], v[30:31], v[36:37] op_sel_hi:[1,0]
	v_pk_mul_f32 v[28:29], v[28:29], v[36:37] op_sel_hi:[1,0]
	v_pk_mul_f32 v[26:27], v[26:27], v[36:37] op_sel_hi:[1,0]
	v_pk_mul_f32 v[24:25], v[24:25], v[36:37] op_sel_hi:[1,0]
	v_pk_mul_f32 v[20:21], v[20:21], v[36:37] op_sel_hi:[1,0]
	v_pk_mul_f32 v[22:23], v[22:23], v[36:37] op_sel_hi:[1,0]
	v_pk_mul_f32 v[16:17], v[16:17], v[36:37] op_sel_hi:[1,0]
	v_pk_mul_f32 v[18:19], v[18:19], v[36:37] op_sel_hi:[1,0]
	v_mul_f32_e32 v33, 0xbfb8aa3b, v28
	v_mul_f32_e32 v36, 0xbfb8aa3b, v29
	v_pk_mul_f32 v[22:23], v[30:31], v[22:23]
	v_pk_mul_f32 v[20:21], v[28:29], v[20:21]
	v_mul_f32_e32 v28, 0xbfb8aa3b, v30
	v_mul_f32_e32 v29, 0xbfb8aa3b, v31
	v_mul_f32_e32 v30, 0xbfb8aa3b, v24
	v_mul_f32_e32 v31, 0xbfb8aa3b, v25
	v_pk_mul_f32 v[16:17], v[24:25], v[16:17]
	v_mul_f32_e32 v24, 0xbfb8aa3b, v26
	v_mul_f32_e32 v25, 0xbfb8aa3b, v27
	v_pk_mul_f32 v[18:19], v[26:27], v[18:19]
	v_exp_f32_e32 v26, v33
	v_exp_f32_e32 v27, v36
	v_exp_f32_e32 v28, v28
	v_exp_f32_e32 v29, v29
	v_exp_f32_e32 v30, v30
	v_exp_f32_e32 v31, v31
	v_exp_f32_e32 v24, v24
	v_exp_f32_e32 v25, v25
	v_add_f32_e32 v26, 1.0, v26
	v_add_f32_e32 v27, 1.0, v27
	v_add_f32_e32 v28, 1.0, v28
	v_add_f32_e32 v29, 1.0, v29
	v_add_f32_e32 v30, 1.0, v30
	v_add_f32_e32 v31, 1.0, v31
	v_add_f32_e32 v33, 1.0, v24
	v_add_f32_e32 v36, 1.0, v25
	v_rcp_f32_e32 v24, v26
	v_rcp_f32_e32 v25, v27
	v_rcp_f32_e32 v26, v28
	v_rcp_f32_e32 v27, v29
	v_rcp_f32_e32 v28, v30
	v_rcp_f32_e32 v29, v31
	v_rcp_f32_e32 v30, v33
	v_rcp_f32_e32 v31, v36
	v_pk_mul_f32 v[20:21], v[20:21], v[24:25]
	v_pk_mul_f32 v[22:23], v[22:23], v[26:27]
	v_pk_mul_f32 v[24:25], v[16:17], v[28:29]
	v_pk_mul_f32 v[26:27], v[18:19], v[30:31]
	v_cvt_pk_bf16_f32 v16, v20, v21
	v_cvt_pk_bf16_f32 v17, v22, v23
	v_cvt_pk_bf16_f32 v18, v24, v25
	v_cvt_pk_bf16_f32 v19, v26, v27
	global_store_dwordx4 v[34:35], v[16:19], off nt
	s_nop 1
	v_mad_i64_i32 v[18:19], s[0:1], v32, s56, v[146:147]
	v_lshl_add_u64 v[18:19], v[18:19], 0, v[148:149]
	s_mov_b64 s[0:1], -1
	v_mov_b32_e32 v16, v200
	v_pk_mul_f32 v[14:15], v[14:15], v[16:17] op_sel_hi:[1,0]
	v_pk_mul_f32 v[12:13], v[12:13], v[16:17] op_sel_hi:[1,0]
	v_pk_mul_f32 v[10:11], v[10:11], v[16:17] op_sel_hi:[1,0]
	v_pk_mul_f32 v[8:9], v[8:9], v[16:17] op_sel_hi:[1,0]
	v_pk_mul_f32 v[4:5], v[4:5], v[16:17] op_sel_hi:[1,0]
	v_pk_mul_f32 v[6:7], v[6:7], v[16:17] op_sel_hi:[1,0]
	v_pk_mul_f32 v[0:1], v[0:1], v[16:17] op_sel_hi:[1,0]
	v_pk_mul_f32 v[2:3], v[2:3], v[16:17] op_sel_hi:[1,0]
	v_mul_f32_e32 v16, 0xbfb8aa3b, v12
	v_mul_f32_e32 v17, 0xbfb8aa3b, v13
	v_pk_mul_f32 v[6:7], v[14:15], v[6:7]
	v_pk_mul_f32 v[4:5], v[12:13], v[4:5]
	v_mul_f32_e32 v12, 0xbfb8aa3b, v14
	v_mul_f32_e32 v13, 0xbfb8aa3b, v15
	v_mul_f32_e32 v14, 0xbfb8aa3b, v8
	v_mul_f32_e32 v15, 0xbfb8aa3b, v9
	v_pk_mul_f32 v[0:1], v[8:9], v[0:1]
	v_mul_f32_e32 v8, 0xbfb8aa3b, v10
	v_mul_f32_e32 v9, 0xbfb8aa3b, v11
	v_pk_mul_f32 v[2:3], v[10:11], v[2:3]
	v_exp_f32_e32 v10, v16
	v_exp_f32_e32 v11, v17
	v_exp_f32_e32 v12, v12
	v_exp_f32_e32 v13, v13
	v_exp_f32_e32 v14, v14
	v_exp_f32_e32 v15, v15
	v_exp_f32_e32 v8, v8
	v_exp_f32_e32 v9, v9
	v_add_f32_e32 v10, 1.0, v10
	v_add_f32_e32 v11, 1.0, v11
	v_add_f32_e32 v12, 1.0, v12
	v_add_f32_e32 v13, 1.0, v13
	v_add_f32_e32 v14, 1.0, v14
	v_add_f32_e32 v15, 1.0, v15
	v_add_f32_e32 v16, 1.0, v8
	v_add_f32_e32 v17, 1.0, v9
	v_rcp_f32_e32 v8, v10
	v_rcp_f32_e32 v9, v11
	v_rcp_f32_e32 v10, v12
	v_rcp_f32_e32 v11, v13
	v_rcp_f32_e32 v12, v14
	v_rcp_f32_e32 v13, v15
	v_rcp_f32_e32 v14, v16
	v_rcp_f32_e32 v15, v17
	v_pk_mul_f32 v[4:5], v[4:5], v[8:9]
	v_pk_mul_f32 v[6:7], v[6:7], v[10:11]
	v_pk_mul_f32 v[8:9], v[0:1], v[12:13]
	v_pk_mul_f32 v[10:11], v[2:3], v[14:15]
	v_cvt_pk_bf16_f32 v0, v4, v5
	v_cvt_pk_bf16_f32 v1, v6, v7
	v_cvt_pk_bf16_f32 v2, v8, v9
	v_cvt_pk_bf16_f32 v3, v10, v11
	global_store_dwordx4 v[18:19], v[0:3], off nt
	s_cbranch_vccnz .LBB0_1107
	s_andn2_b64 vcc, exec, s[6:7]
	s_cbranch_vccnz .LBB0_1106
	s_barrier
	s_branch .LBB0_1106
